# phase C job prologue: Q rows, pass-1 stages and pass-2 prologue stages issued in one round trip
# baseline (speedup 1.0000x reference)
.LBB0_481:
	s_lshl_b32 s3, s25, 2
	s_and_b32 s60, s3, -16
	v_subrev_u32_e32 v0, s60, v96
	s_and_b32 s2, s25, 1
	v_add_u32_e32 v107, 0x3ff0, v0
	v_lshl_or_b32 v87, s2, 2, v98
	v_or_b32_e32 v0, v107, v97
	s_lshl_b32 s2, s25, 13
	s_and_b32 s84, s2, 0x4000
	v_ashrrev_i32_e32 v1, 31, v0
	v_lshl_add_u64 v[88:89], v[0:1], 0, s[84:85]
	v_mov_b64_e32 v[0:1], s[36:37]
	v_mad_u64_u32 v[0:1], s[2:3], v88, s10, v[0:1]
	v_mad_i32_i24 v1, v89, s10, v1
	v_lshlrev_b32_e32 v128, 7, v87
	v_lshl_add_u64 v[0:1], v[0:1], 0, v[128:129]
	v_mov_b32_e32 v85, v129
	v_lshl_add_u64 v[0:1], v[0:1], 0, v[84:85]
	s_mov_b64 s[2:3], 0x4000800
	v_lshl_add_u64 v[4:5], v[0:1], 0, s[2:3]
	v_add_co_u32_e32 v0, vcc, s11, v0
	s_sub_i32 s3, 0x3fe0, s60
	s_nop 0
	v_addc_co_u32_e32 v1, vcc, 0, v1, vcc
	global_load_dwordx4 v[0:3], v[0:1], off offset:2048
	s_nop 0
	global_load_dwordx4 v[4:7], v[4:5], off offset:64
	v_mul_u32_u24_e32 v134, 3, v87
	v_lshlrev_b64 v[132:133], 7, v[88:89]
	v_lshl_add_u64 v[132:133], s[40:41], 0, v[132:133]
	v_lshlrev_b32_e32 v134, 2, v134
	v_mov_b32_e32 v135, 0
	v_lshl_add_u64 v[132:133], v[132:133], 0, v[134:135]
	global_load_dword v136, v[132:133], off
	s_ashr_i32 s3, s3, 4
	s_add_i32 s3, s3, 32
	s_lshr_b32 s3, s3, 5
	s_and_b32 s72, s94, 3
	s_add_i32 s2, s60, 0xffffc000
	s_add_i32 s3, s3, -1
	s_cmpk_lt_i32 s2, 0xffe1
	s_cselect_b32 s66, s3, -1
	s_cmp_lt_i32 s66, 0
	s_cbranch_scc1 .Lp4_noattn
	s_and_b32 s2, s25, 3
	s_lshl_b32 s74, s2, 17
	s_add_u32 s64, s26, s74
	s_addc_u32 s65, s27, 0
	v_ashrrev_i32_e32 v42, 3, v218
	v_ashrrev_i32_e32 v43, 31, v42
	v_lshlrev_b64 v[44:45], 7, v[42:43]
	v_lshl_add_u64 v[44:45], s[64:65], 0, v[44:45]
	v_lshlrev_b32_e32 v42, 4, v218
	v_and_b32_e32 v128, 0x70, v42
	v_lshl_add_u64 v[40:41], v[44:45], 0, v[128:129]
	s_mov_b64 vcc, 0x1000
	v_lshl_add_u64 v[44:45], v[40:41], 0, vcc
	s_mov_b64 vcc, 0x2000
	v_lshl_add_u64 v[50:51], v[40:41], 0, vcc
	s_mov_b64 vcc, 0x3000
	v_lshl_add_u64 v[52:53], v[40:41], 0, vcc
	global_load_dwordx4 v[8:11], v[40:41], off
	global_load_dwordx4 v[12:15], v[44:45], off
	global_load_dwordx4 v[16:19], v[50:51], off
	global_load_dwordx4 v[20:23], v[52:53], off
	global_load_dwordx4 v[138:141], v[40:41], off
	global_load_dwordx4 v[146:149], v[44:45], off
	global_load_dwordx4 v[154:157], v[50:51], off
	global_load_dwordx4 v[158:161], v[52:53], off
	v_ashrrev_i32_e32 v42, 2, v218
	v_ashrrev_i32_e32 v43, 31, v42
	v_lshlrev_b64 v[170:171], 11, v[42:43]
	s_add_u32 vcc_lo, s28, s74
	s_addc_u32 vcc_hi, s29, 0
	v_lshl_add_u64 v[170:171], vcc, 0, v[170:171]
	v_lshlrev_b32_e32 v42, 4, v218
	v_and_b32_e32 v128, 48, v42
	v_lshl_add_u64 v[170:171], v[170:171], 0, v[128:129]
	global_load_dwordx4 v[142:145], v[170:171], off
	global_load_dwordx4 v[150:153], v[170:171], off offset:64
	global_load_dwordx4 v[162:165], v[170:171], off offset:128
	global_load_dwordx4 v[166:169], v[170:171], off offset:192
	s_cmp_gt_u32 s66, 1
	s_cselect_b64 s[62:63], -1, 0
	s_waitcnt vmcnt(13)
	ds_write_b128 v99, v[0:3] offset:32768
	ds_write_b128 v99, v[4:7] offset:32832
	v_mov_b32_e32 v3, v218
	v_ashrrev_i32_e32 v0, 3, v3
	v_lshlrev_b32_e32 v4, 4, v3
	s_branch .LBB0_484
.Lp4_noattn:
	s_waitcnt vmcnt(1)
	ds_write_b128 v99, v[0:3] offset:32768
	s_waitcnt vmcnt(0)
	ds_write_b128 v99, v[4:7] offset:32832
	s_branch .LBB0_570
.LBB0_484:
	v_and_b32_e32 v2, 15, v3
	v_bfe_u32 v1, v3, 4, 2
	v_lshlrev_b32_e32 v0, 7, v0
	v_xor_b32_e32 v3, v4, v3
	s_movk_i32 s2, 0x70
	v_and_or_b32 v42, v3, s2, v0
	v_mul_u32_u24_e32 v0, 0x90, v2
	v_lshlrev_b32_e32 v3, 4, v1
	v_add3_u32 v0, v95, v0, v3
	ds_read_b128 v[24:27], v0 offset:32768
	ds_read_b128 v[28:31], v0 offset:32832
	s_cmp_gt_u32 s66, 3
	v_readfirstlane_b32 s67, v107
	v_mov_b32_e32 v32, 0x3f803f80
	s_cselect_b64 s[60:61], -1, 0
	s_cmp_lt_u32 s66, 4
	s_waitcnt vmcnt(11)
	ds_write_b128 v42, v[8:11]
	s_waitcnt vmcnt(10)
	ds_write_b128 v42, v[12:15] offset:8192
	s_cbranch_scc1 .LBB0_486
	v_add_co_u32_e32 v4, vcc, 0x4000, v40
	s_nop 1
	v_addc_co_u32_e32 v5, vcc, 0, v41, vcc
	v_add_co_u32_e32 v6, vcc, 0x5000, v40
	s_nop 1
	v_addc_co_u32_e32 v7, vcc, 0, v41, vcc
	global_load_dwordx4 v[8:11], v[4:5], off
	global_load_dwordx4 v[12:15], v[6:7], off

.LBB0_514:
	v_mov_b32_e32 v49, v218
	s_add_u32 s2, s28, s74
	v_ashrrev_i32_e32 v4, 3, v49
	v_ashrrev_i32_e32 v5, 31, v4
	v_lshlrev_b64 v[0:1], 7, v[4:5]
	v_lshlrev_b32_e32 v40, 4, v49
	v_lshl_add_u64 v[0:1], s[64:65], 0, v[0:1]
	v_and_b32_e32 v128, 0x70, v40
	v_ashrrev_i32_e32 v6, 2, v49
	v_lshl_add_u64 v[90:91], v[0:1], 0, v[128:129]
	v_ashrrev_i32_e32 v7, 31, v6
	s_addc_u32 s3, s29, 0
	v_lshlrev_b64 v[0:1], 11, v[6:7]
	s_waitcnt vmcnt(0)
	v_add_co_u32_e32 v12, vcc, 0x1000, v90
	v_lshl_add_u64 v[2:3], s[2:3], 0, v[0:1]
	v_and_b32_e32 v128, 48, v40
	v_addc_co_u32_e32 v13, vcc, 0, v91, vcc
	v_lshl_add_u64 v[2:3], v[2:3], 0, v[128:129]
	s_nop 0
	s_nop 0
	s_andn2_b64 vcc, exec, s[62:63]
	s_cbranch_vccnz .LBB0_516
	v_mov_b64_e32 v[20:21], v[154:155]
	v_mov_b64_e32 v[22:23], v[156:157]
	v_mov_b64_e32 v[28:29], v[158:159]
	v_mov_b64_e32 v[30:31], v[160:161]
	v_mov_b64_e32 v[32:33], v[162:163]
	v_mov_b64_e32 v[34:35], v[164:165]
	v_mov_b64_e32 v[36:37], v[166:167]
	v_mov_b64_e32 v[38:39], v[168:169]
.LBB0_516:
	v_and_b32_e32 v5, 15, v49
	v_bfe_u32 v85, v49, 4, 2
	v_lshlrev_b32_e32 v4, 7, v4
	v_xor_b32_e32 v7, v40, v49
	s_movk_i32 s2, 0x70
	v_and_or_b32 v108, v7, s2, v4
	v_mul_u32_u24_e32 v7, 0x90, v5
	v_lshlrev_b32_e32 v40, 4, v85
	v_lshlrev_b32_e32 v4, 6, v6
	v_lshrrev_b32_e32 v6, 2, v49
	v_add3_u32 v7, v95, v7, v40
	v_and_b32_e32 v6, 12, v6
	s_movk_i32 s2, 0x1320
	ds_read_b128 v[40:43], v7 offset:32768
	ds_read_b128 v[44:47], v7 offset:32832
	v_lshrrev_b32_e64 v6, v6, s2
	v_xor_b32_e32 v6, v6, v49
	v_lshlrev_b32_e32 v6, 4, v6
	v_readfirstlane_b32 s62, v107
	v_mov_b32_e32 v7, 0x3f803f80
	v_and_or_b32 v109, v6, 48, v4
	s_andn2_b64 vcc, exec, s[60:61]
	s_waitcnt vmcnt(3)
	ds_write_b128 v108, v[138:141]
	s_waitcnt vmcnt(1)
	ds_write_b128 v108, v[146:149] offset:8192
	ds_write_b128 v109, v[142:145] offset:4096
	s_waitcnt vmcnt(0)
	ds_write_b128 v109, v[150:153] offset:12288
	s_cbranch_vccnz .LBB0_518
	v_add_co_u32_e32 v6, vcc, 0x4000, v90
	s_nop 1
	v_addc_co_u32_e32 v7, vcc, 0, v91, vcc
	v_add_co_u32_e32 v12, vcc, 0x5000, v90
	s_nop 1
	v_addc_co_u32_e32 v13, vcc, 0, v91, vcc
	global_load_dwordx4 v[8:11], v[6:7], off
	s_nop 0
	global_load_dwordx4 v[12:15], v[12:13], off
	s_nop 0
	global_load_dwordx4 v[16:19], v[2:3], off offset:256
	global_load_dwordx4 v[24:27], v[2:3], off offset:320
